# DA loop: global tile loads use SGPR-base + 32-bit VGPR offset (saddr) form, removing 8 64-bit VALU address ops per iteration
# baseline (speedup 1.0000x reference)
; __device__ __forceinline__ int vpos_of(int c) { const int c16 = c & 15; return (c & ~15) + 8 * ((c16 >> 2) & 1) + (c16 & 3) + 4 * (c16 >> 3); }
; __device__ __forceinline__ int vsw(int d) { return ((d >> 3) & 1) | (((d >> 4) & 1) << 1) | ((((d >> 1) ^ (d >> 5)) & 1) << 2); }
; __device__ __forceinline__ void da_unit(LAS unsigned char* lds, const bf16_t* __restrict__ proj, bf16_t* __restrict__ y, int unit,
;                                         const float* __restrict__ t5, float lam, float one_m_li, const float* __restrict__ subg) {
;     ...
;     const bf16_t* qp = proj + (rowbase + q) * 4096 + 2048 + h * 128 + mp * 64 + hh * 8;
;     bf16x8 qf[4];
; #pragma unroll
;     for (int ks = 0; ks < 4; ++ks) qf[ks] = *(const bf16x8*)(qp + ks * 16);
;     const int kc = tid & 15, kr = tid >> 4;
;     const bf16_t* kvbase = proj + rowbase * 4096 + 2560 + h * 128;
;     const unsigned kgo = (unsigned)(kr * 4096 + kc * 8), vgo = (unsigned)(2 * kr * 4096 + 512 + kc * 8);
;     const int vps = vpos_of(2 * kr), vch = vps >> 3, vswc = vsw(8 * kc);
;     const unsigned kw = kr * DA_KROW + kc * 16, vwb = DA_V_OFF + (8 * kc) * DA_VROW + ((vps & 7) >> 1) * 4;
;     const unsigned vwA = vwb + ((vch ^ vswc) << 4), vwB = vwb + ((vch ^ vswc ^ 4) << 4);
;     const unsigned vrd = (unsigned)(DA_V_OFF + l31 * DA_VROW) ^ (unsigned)((hh ^ vsw(l31)) << 4);
;     u32x4 kreg0, kreg1, vreg0, vreg1;
;     ...
;     f32x16 o[4];
; #pragma unroll
;     for (int t = 0; t < 4; ++t)
; #pragma unroll
;         for (int r = 0; r < 16; ++r) o[t][r] = 0.f;
;     float m = M_INIT, l = 0.f;
;     {
;       const u32x4 a0 = *(const u32x4*)(kvbase + kgo), a1 = *(const u32x4*)(kvbase + (kgo + 32u * 4096u)), a2 = *(const u32x4*)(kvbase + vgo), a3 = *(const u32x4*)(kvbase + (vgo + 4096u));
;       DA_LOAD(1);
;       const u32x4 b0 = kreg0, b1 = kreg1, b2 = vreg0, b3 = vreg1;
;       DA_LOAD(2);
;       const u32x4 c0 = kreg0, c1 = kreg1, c2 = vreg0, c3 = vreg1;
;       kreg0 = a0; kreg1 = a1; vreg0 = a2; vreg1 = a3; DA_STORE(lds);
;       kreg0 = b0; kreg1 = b1; vreg0 = b2; vreg1 = b3; DA_STORE(lds + DA_BUF);
;       kreg0 = c0; kreg1 = c1; vreg0 = c2; vreg1 = c3; }
;     __syncthreads();
.LBB0_161:
	s_or_b64 exec, exec, s[30:31]
	s_ashr_i32 s30, s73, 7
	s_lshl_b32 s4, s73, 7
	s_ashr_i32 s7, s1, 2
	s_bfe_u32 s5, s1, 0x10006
	s_ashr_i32 s31, s30, 31
	s_and_b32 s97, s4, 0xf80
	s_andn2_b32 s7, s7, 31
	s_and_b32 s6, s72, 0xf80
	s_lshl_b64 s[76:77], s[30:31], 12
	s_add_i32 s8, s7, s97
	s_lshl_b32 s4, s9, 7
	s_lshl_b32 s40, s9, 8
	s_lshl_b32 s36, s5, 7
	s_lshl_b64 s[30:31], s[30:31], 25
	s_add_u32 s9, s60, s30
	s_waitcnt vmcnt(1)
	v_and_b32_e32 v1, 15, v0
	s_addc_u32 s10, s61, s31
	v_ashrrev_i32_e32 v46, 4, v0
	s_add_u32 s9, s9, s40
	s_waitcnt vmcnt(0)
	v_lshlrev_b32_e32 v2, 3, v1
	s_addc_u32 s10, s10, 0
	v_lshl_or_b32 v152, v46, 12, v2
	s_add_u32 s30, s9, 0x1400
	v_lshl_or_b32 v18, v46, 13, v2
	v_add_u32_e32 v168, 0x20000, v152
	v_mov_b32_e32 v169, v153
	s_addc_u32 s31, s10, 0
	v_lshlrev_b64 v[34:35], 1, v[152:153]
	v_lshlrev_b32_e32 v254, 1, v152
	v_lshlrev_b64 v[36:37], 1, v[168:169]
	v_lshlrev_b32_e32 v169, 1, v168
	v_or_b32_e32 v170, 0x1200, v18
	v_mov_b32_e32 v171, v153
	v_lshl_add_u64 v[2:3], s[30:31], 0, v[34:35]
	v_lshl_add_u64 v[6:7], s[30:31], 0, v[36:37]
	v_mov_b32_e32 v19, v153
	v_lshlrev_b64 v[38:39], 1, v[170:171]
	v_lshlrev_b32_e32 v171, 1, v170
	global_load_dwordx4 v[2:5], v[2:3], off
	s_nop 0
	global_load_dwordx4 v[6:9], v[6:7], off
	v_lshl_add_u64 v[10:11], v[18:19], 1, s[30:31]
	v_lshl_add_u64 v[14:15], s[30:31], 0, v[38:39]
	global_load_dwordx4 v[10:13], v[10:11], off offset:1024
	s_nop 0
	global_load_dwordx4 v[14:17], v[14:15], off
	v_or_b32_e32 v172, 0x200, v18
	v_mov_b32_e32 v173, v153
	s_add_u32 s78, s9, 0x81400
	s_addc_u32 s79, s10, 0
	v_lshlrev_b64 v[40:41], 1, v[172:173]
	v_lshlrev_b32_e32 v173, 1, v172
	v_lshl_add_u64 v[18:19], s[78:79], 0, v[34:35]
	v_lshl_add_u64 v[22:23], s[78:79], 0, v[36:37]
	v_lshl_add_u64 v[26:27], s[78:79], 0, v[40:41]
	v_lshl_add_u64 v[30:31], s[78:79], 0, v[38:39]
	global_load_dwordx4 v[18:21], v[18:19], off
	s_nop 0
	global_load_dwordx4 v[22:25], v[22:23], off
	s_nop 0
	global_load_dwordx4 v[26:29], v[26:27], off
	s_nop 0
	global_load_dwordx4 v[30:33], v[30:31], off
	v_and_b32_e32 v182, 31, v0
	v_or_b32_e32 v42, s8, v182
	v_ashrrev_i32_e32 v43, 31, v42
	v_lshl_add_u64 v[164:165], s[76:77], 0, v[42:43]
	v_lshlrev_b64 v[42:43], 13, v[164:165]
	v_lshl_add_u64 v[166:167], s[60:61], 0, v[42:43]
	v_bfe_u32 v196, v0, 5, 1
	v_lshl_add_u64 v[42:43], v[166:167], 0, s[40:41]
	s_mov_b32 s37, s41
	v_lshl_add_u64 v[42:43], v[42:43], 0, s[36:37]
	v_lshlrev_b32_e32 v174, 4, v196
	v_mov_b32_e32 v175, v153
	v_lshl_add_u64 v[42:43], v[42:43], 0, v[174:175]
	s_mov_b64 s[76:77], 0x1000
	s_movk_i32 s11, 0x1000
	v_lshl_add_u64 v[44:45], v[42:43], 0, s[76:77]
	v_add_co_u32_e32 v42, vcc, s11, v42
	s_movk_i32 s11, 0x110
	s_nop 0
	v_addc_co_u32_e32 v43, vcc, 0, v43, vcc
	global_load_dwordx4 v[96:99], v[44:45], off offset:32
	global_load_dwordx4 v[100:103], v[44:45], off offset:64
	global_load_dwordx4 v[104:107], v[42:43], off
	global_load_dwordx4 v[108:111], v[44:45], off offset:96
	v_lshlrev_b32_e32 v42, 1, v46
	v_lshlrev_b32_e32 v43, 2, v46
	v_and_b32_e32 v42, -14, v42
	v_and_or_b32 v43, v43, 8, v42
	v_lshrrev_b32_e32 v43, 3, v43
	v_bitop3_b32 v43, v43, v0, 7 bitop3:0x78
	v_bfe_u32 v45, v0, 3, 2
	v_lshlrev_b32_e32 v0, 1, v0
	v_and_b32_e32 v0, 4, v0
	v_bitop3_b32 v0, v0, v196, v45 bitop3:0x36
	s_add_u32 s78, s9, 0x101400
	v_lshlrev_b32_e32 v0, 4, v0
	v_mul_lo_u32 v45, v46, s11
	s_addc_u32 s79, s10, 0
	v_lshlrev_b32_e32 v44, 10, v1
	v_lshl_add_u32 v175, v1, 4, v45
	v_lshl_or_b32 v45, v182, 7, v0
	v_lshl_add_u64 v[0:1], s[78:79], 0, v[34:35]
	v_lshl_add_u64 v[34:35], s[78:79], 0, v[36:37]
	global_load_dwordx4 v[116:119], v[0:1], off
	global_load_dwordx4 v[120:123], v[34:35], off
	v_lshl_add_u64 v[0:1], s[78:79], 0, v[40:41]
	v_lshl_add_u64 v[34:35], s[78:79], 0, v[38:39]
	global_load_dwordx4 v[112:115], v[0:1], off
	global_load_dwordx4 v[124:127], v[34:35], off
	v_and_or_b32 v42, v46, 4, v42
	v_lshlrev_b32_e32 v42, 1, v42
	v_lshlrev_b32_e32 v43, 4, v43
	v_and_or_b32 v1, v42, 12, v44
	v_add_u32_e32 v0, 0, v175
	v_add_u32_e32 v184, v1, v43
	s_waitcnt vmcnt(15)
	ds_write_b128 v0, v[2:5]
	s_waitcnt vmcnt(14)
	ds_write_b128 v0, v[6:9] offset:8704
	v_add_u32_e32 v2, 0, v184
	v_xad_u32 v185, v43, 64, v1
	s_waitcnt vmcnt(12)
	v_perm_b32 v3, v14, v10, s66
	v_perm_b32 v4, v14, v10, s67
	v_add_u32_e32 v5, 0x4400, v2
	v_add_u32_e32 v1, 0, v185
	ds_write2_b32 v5, v3, v4 offset1:32
	v_perm_b32 v3, v15, v11, s66
	v_perm_b32 v4, v15, v11, s67
	v_add_u32_e32 v6, 0x4400, v1
	ds_write2_b32 v6, v3, v4 offset0:64 offset1:96
	v_perm_b32 v3, v16, v12, s66
	v_perm_b32 v4, v16, v12, s67
	ds_write2_b32 v5, v3, v4 offset0:128 offset1:160
	v_perm_b32 v3, v17, v13, s66
	v_perm_b32 v4, v17, v13, s67
	ds_write2_b32 v6, v3, v4 offset0:192 offset1:224
	s_waitcnt vmcnt(11)
	ds_write_b128 v0, v[18:21] offset:33792
	s_waitcnt vmcnt(10)
	ds_write_b128 v0, v[22:25] offset:42496
	s_waitcnt vmcnt(8)
	v_perm_b32 v0, v30, v26, s66
	v_perm_b32 v3, v30, v26, s67
	v_add_u32_e32 v2, 0xc800, v2
	ds_write2_b32 v2, v0, v3 offset1:32
	v_perm_b32 v0, v31, v27, s66
	v_perm_b32 v3, v31, v27, s67
	v_add_u32_e32 v1, 0xc800, v1
	ds_write2_b32 v1, v0, v3 offset0:64 offset1:96
	v_perm_b32 v0, v32, v28, s66
	v_perm_b32 v3, v32, v28, s67
	v_mul_u32_u24_e32 v186, 0x110, v182
	s_add_i32 s9, s36, 0
	ds_write2_b32 v2, v0, v3 offset0:128 offset1:160
	v_perm_b32 v0, v33, v29, s66
	v_perm_b32 v2, v33, v29, s67
	v_add3_u32 v187, s9, v186, v174
	ds_write2_b32 v1, v0, v2 offset0:192 offset1:224
	s_waitcnt lgkmcnt(0)
	s_barrier
; #define DA_LOAD(j) do { const bf16_t* t_ = kvbase + (size_t)(j) * 64 * 4096; kreg0 = *(const u32x4*)(t_ + kgo); kreg1 = *(const u32x4*)(t_ + (kgo + 32u * 4096u)); vreg0 = *(const u32x4*)(t_ + vgo); vreg1 = *(const u32x4*)(t_ + (vgo + 4096u)); } while (0)
; #define DA_KLD(KF_, Bk, sub) do { const LAS unsigned char* kp_ = (Bk) + (32 * (sub) + l31) * DA_KROW + mp * 128 + hh * 16; \
;         _Pragma("unroll") for (int ks = 0; ks < 4; ++ks) KF_[ks] = *(const LAS bf16x8*)(kp_ + ks * 32); } while (0)
; __device__ __forceinline__ float rowmax16(const f32x16& z) {
;     float a = fmaxf(fmaxf(z[0], z[1]), z[2]), b = fmaxf(fmaxf(z[3], z[4]), z[5]);
;     a = fmaxf(fmaxf(a, z[6]), z[7]); b = fmaxf(fmaxf(b, z[8]), z[9]); a = fmaxf(fmaxf(a, z[10]), z[11]); b = fmaxf(fmaxf(b, z[12]), z[13]); a = fmaxf(fmaxf(a, z[14]), z[15]);
;     return fmaxf(a, b);
; }
; __device__ __forceinline__ void da_unit(LAS unsigned char* lds, const bf16_t* __restrict__ proj, bf16_t* __restrict__ y, int unit,
;                                         const float* __restrict__ t5, float lam, float one_m_li, const float* __restrict__ subg) {
;     ...
;     f32x16 o[4];
; #pragma unroll
;     for (int t = 0; t < 4; ++t)
; #pragma unroll
;         for (int r = 0; r < 16; ++r) o[t][r] = 0.f;
;     float m = M_INIT, l = 0.f;
;     {
;       const u32x4 a0 = *(const u32x4*)(kvbase + kgo), a1 = *(const u32x4*)(kvbase + (kgo + 32u * 4096u)), a2 = *(const u32x4*)(kvbase + vgo), a3 = *(const u32x4*)(kvbase + (vgo + 4096u));
;       DA_LOAD(1);
;       const u32x4 b0 = kreg0, b1 = kreg1, b2 = vreg0, b3 = vreg1;
;       DA_LOAD(2);
;       const u32x4 c0 = kreg0, c1 = kreg1, c2 = vreg0, c3 = vreg1;
;       kreg0 = a0; kreg1 = a1; vreg0 = a2; vreg1 = a3; DA_STORE(lds);
;       kreg0 = b0; kreg1 = b1; vreg0 = b2; vreg1 = b3; DA_STORE(lds + DA_BUF);
;       kreg0 = c0; kreg1 = c1; vreg0 = c2; vreg1 = c3; }
;     __syncthreads();
;     f32x16 sa, sb;
;     bf16x8 kF[4], vF[4], vS[4];
;     u32x4 pp0 = {0u, 0u, 0u, 0u}, pp1 = {0u, 0u, 0u, 0u}, pc0, pc1;
;     int bcur = 0, bprev = 0, bnext = DA_BUF, bnn = 2 * DA_BUF;
;     bool near = (63 >= qblk - 128) && (0 <= qblk + 255); float bc = tbl[0];
;     int dtoff = DA_DL_OFF;
;     DA_KLD(kF, lds, 0); DA_QKM(sa, kF);
;     DA_VLD(vF, lds + bprev, 1, 0);
	ds_read_b128 v[0:3], v187
	s_waitcnt vmcnt(5) lgkmcnt(0)
	v_mfma_f32_32x32x16_bf16 v[64:79], v[0:3], v[104:107], 0
	s_add_i32 s9, 0, 0x18c00
	v_mov_b32_e32 v4, s9
	ds_read_b32 v177, v4
	ds_read_b128 v[4:7], v187 offset:32
	ds_read_b128 v[8:11], v187 offset:64
	ds_read_b128 v[12:15], v187 offset:96
	v_add_u32_e32 v188, 0x4400, v45
	s_mov_b32 s76, 0
	v_add_u32_e32 v183, 0, v188
	s_mov_b32 s77, s76
	s_waitcnt lgkmcnt(2)
	v_mfma_f32_32x32x16_bf16 v[64:79], v[4:7], v[96:99], v[64:79]
	v_xor_b32_e32 v0, 64, v183
	s_mov_b32 s78, s76
	s_mov_b32 s79, s76
	s_mov_b32 s80, s76
	s_mov_b32 s81, s76
	s_mov_b32 s82, s76
	s_mov_b32 s83, s76
	s_waitcnt lgkmcnt(1)
	v_mfma_f32_32x32x16_bf16 v[64:79], v[8:11], v[100:103], v[64:79]
	s_mov_b32 s84, s76
	s_mov_b32 s85, s76
	s_mov_b32 s86, s76
	s_mov_b32 s87, s76
	s_mov_b32 s88, s76
	s_mov_b32 s89, s76
	s_mov_b32 s90, s76
	s_waitcnt vmcnt(4) lgkmcnt(0)
	v_mfma_f32_32x32x16_bf16 v[64:79], v[12:15], v[108:111], v[64:79]
	s_mov_b32 s91, s76
	v_mov_b64_e32 v[48:49], s[76:77]
	ds_read_b128 v[140:143], v0
	ds_read_b128 v[132:135], v0 offset:8192
	ds_read_b128 v[136:139], v183 offset:4096
	ds_read_b128 v[128:131], v183 offset:12288
	v_mov_b64_e32 v[50:51], s[78:79]
	v_mov_b64_e32 v[52:53], s[80:81]
	v_mov_b64_e32 v[54:55], s[82:83]
	v_mov_b64_e32 v[56:57], s[84:85]
	v_mov_b64_e32 v[58:59], s[86:87]
	v_mov_b64_e32 v[60:61], s[88:89]
	v_mov_b64_e32 v[62:63], s[90:91]
	s_add_i32 s80, s6, s7
	v_or_b32_e32 v0, s80, v182
	v_lshlrev_b32_e32 v0, 2, v0
	v_sub_u32_e32 v0, v174, v0
	v_add_u32_e32 v189, 0, v0
	v_mov_b64_e32 v[32:33], v[48:49]
	v_mov_b64_e32 v[16:17], v[48:49]
	v_mov_b64_e32 v[0:1], v[48:49]
	s_mov_b32 s37, 1
	s_add_i32 s40, s8, 0x9e
	s_add_i32 s77, s8, 0x7e
	v_mov_b32_e32 v176, 0xf149f2ca
	s_mov_b32 s6, 0x19800
	s_mov_b32 s83, 0x10800
	s_mov_b32 s82, 0x8400
	v_mov_b32_e32 v178, 0
	s_movk_i32 s81, 0x80
	v_mov_b32_e32 v148, 0
	v_mov_b32_e32 v149, 0
	v_mov_b32_e32 v150, 0
	v_mov_b32_e32 v151, 0
	v_mov_b32_e32 v144, 0
	v_mov_b32_e32 v145, 0
	v_mov_b32_e32 v146, 0
	v_mov_b32_e32 v147, 0
	v_mov_b64_e32 v[34:35], v[50:51]
	v_mov_b64_e32 v[36:37], v[52:53]
	v_mov_b64_e32 v[38:39], v[54:55]
	v_mov_b64_e32 v[40:41], v[56:57]
	v_mov_b64_e32 v[42:43], v[58:59]
	v_mov_b64_e32 v[44:45], v[60:61]
	v_mov_b64_e32 v[46:47], v[62:63]
	v_mov_b64_e32 v[18:19], v[50:51]
	v_mov_b64_e32 v[20:21], v[52:53]
	v_mov_b64_e32 v[22:23], v[54:55]
	v_mov_b64_e32 v[24:25], v[56:57]
	v_mov_b64_e32 v[26:27], v[58:59]
	v_mov_b64_e32 v[28:29], v[60:61]
	v_mov_b64_e32 v[30:31], v[62:63]
	v_mov_b64_e32 v[2:3], v[50:51]
	v_mov_b64_e32 v[4:5], v[52:53]
	v_mov_b64_e32 v[6:7], v[54:55]
	v_mov_b64_e32 v[8:9], v[56:57]
	v_mov_b64_e32 v[10:11], v[58:59]
	v_mov_b64_e32 v[12:13], v[60:61]
	v_mov_b64_e32 v[14:15], v[62:63]
	s_mov_b32 s7, s76
	s_mov_b32 s8, s76

; #define DA_LOAD(j) do { const bf16_t* t_ = kvbase + (size_t)(j) * 64 * 4096; kreg0 = *(const u32x4*)(t_ + kgo); kreg1 = *(const u32x4*)(t_ + (kgo + 32u * 4096u)); vreg0 = *(const u32x4*)(t_ + vgo); vreg1 = *(const u32x4*)(t_ + (vgo + 4096u)); } while (0)
; __device__ __forceinline__ void da_unit(LAS unsigned char* lds, const bf16_t* __restrict__ proj, bf16_t* __restrict__ y, int unit,
;                                         const float* __restrict__ t5, float lam, float one_m_li, const float* __restrict__ subg) {
;     ...
; #pragma unroll 2
;     for (int j = 0; j < 64; ++j) {
;         const int j1 = j + 1;
;         const bool near1 = (64 * j1 + 63 >= qblk - 128) && (64 * j1 <= qblk + 255);
;         const float bc1 = tbl[(64 * j1 > qblk) ? 256 : 0]; const int dtoff1 = (64 * j1 > qblk) ? DA_DR_OFF : DA_DL_OFF;
;         DA_STEP(sa, sb, pp0, pp1, pc0, pc1, lds + bprev, 1, lds + bcur, 1, j * 64, lds + bcur, 0);
;         __syncthreads();
;         DA_STORE(lds + bnn); { const int jl = j + 3 < 64 ? j + 3 : 63; DA_LOAD(jl); }
;         DA_STEP(sb, sa, pc0, pc1, pp0, pp1, lds + bcur, 0, lds + bnext, 0, j * 64 + 32, lds + bcur, 1);
.LBB0_167:
	s_add_i32 s9, s83, 0
	s_add_i32 s8, s37, -1
	v_add_u32_e32 v64, s9, v175
	s_waitcnt lgkmcnt(0)
	s_barrier
	s_waitcnt vmcnt(3)
	ds_write_b128 v64, v[116:119]
	s_waitcnt vmcnt(2)
	ds_write_b128 v64, v[120:123] offset:8704
	v_add_u32_e32 v64, s9, v184
	s_min_u32 s8, s8, 60
	s_waitcnt vmcnt(0)
	v_perm_b32 v65, v124, v112, s66
	v_perm_b32 v66, v124, v112, s67
	v_add_u32_e32 v64, 0x4400, v64
	s_lshl_b32 s8, s8, 19
	ds_write2_b32 v64, v65, v66 offset1:32
	v_add_u32_e32 v65, s9, v185
	s_add_u32 s8, s30, s8
	v_perm_b32 v66, v125, v113, s66
	v_perm_b32 v67, v125, v113, s67
	v_add_u32_e32 v65, 0x4400, v65
	s_addc_u32 s9, s31, 0
	ds_write2_b32 v65, v66, v67 offset0:64 offset1:96
	v_perm_b32 v66, v126, v114, s66
	v_perm_b32 v67, v126, v114, s67
	s_add_u32 s8, s8, 0x180000
	ds_write2_b32 v64, v66, v67 offset0:128 offset1:160
	v_perm_b32 v64, v127, v115, s66
	v_perm_b32 v66, v127, v115, s67
	s_addc_u32 s9, s9, 0
	ds_write2_b32 v65, v64, v66 offset0:192 offset1:224
	global_load_dwordx4 v[116:119], v254, s[8:9]
	global_load_dwordx4 v[124:127], v169, s[8:9]
	global_load_dwordx4 v[112:115], v173, s[8:9]
	global_load_dwordx4 v[120:123], v171, s[8:9]
	s_cmp_gt_i32 s7, s77
	s_cselect_b64 s[8:9], -1, 0
	s_sub_i32 s7, s86, 63
	s_cmpk_gt_i32 s7, 0x7f
	s_cselect_b64 s[88:89], -1, 0
	s_or_b64 s[8:9], s[8:9], s[88:89]
	s_and_b64 vcc, exec, s[8:9]
	s_cbranch_vccnz .LBB0_169
	s_addk_i32 s6, 0x500
	v_add_u32_e32 v78, s6, v189
	ds_read2_b32 v[64:65], v78 offset0:48 offset1:49
	ds_read2_b32 v[66:67], v78 offset0:50 offset1:51
	ds_read2_b32 v[68:69], v78 offset0:56 offset1:57
	ds_read2_b32 v[70:71], v78 offset0:58 offset1:59
	ds_read2_b32 v[72:73], v78 offset0:32 offset1:33
	ds_read2_b32 v[74:75], v78 offset0:34 offset1:35
	ds_read2_b32 v[76:77], v78 offset0:40 offset1:41
	ds_read2_b32 v[78:79], v78 offset0:42 offset1:43
	s_waitcnt lgkmcnt(4)
	v_pk_add_f32 v[94:95], v[94:95], v[70:71]
	v_pk_add_f32 v[92:93], v[92:93], v[68:69]
	v_pk_add_f32 v[90:91], v[90:91], v[66:67]
	v_pk_add_f32 v[88:89], v[88:89], v[64:65]
	s_waitcnt lgkmcnt(0)
	v_pk_add_f32 v[86:87], v[86:87], v[78:79]
	v_pk_add_f32 v[84:85], v[84:85], v[76:77]
	v_pk_add_f32 v[82:83], v[82:83], v[74:75]
	v_pk_add_f32 v[80:81], v[80:81], v[72:73]

; #define DA_LOAD(j) do { const bf16_t* t_ = kvbase + (size_t)(j) * 64 * 4096; kreg0 = *(const u32x4*)(t_ + kgo); kreg1 = *(const u32x4*)(t_ + (kgo + 32u * 4096u)); vreg0 = *(const u32x4*)(t_ + vgo); vreg1 = *(const u32x4*)(t_ + (vgo + 4096u)); } while (0)
; __device__ __forceinline__ void da_unit(LAS unsigned char* lds, const bf16_t* __restrict__ proj, bf16_t* __restrict__ y, int unit,
;                                         const float* __restrict__ t5, float lam, float one_m_li, const float* __restrict__ subg) {
;     ...
; #pragma unroll 2
;     for (int j = 0; j < 64; ++j) {
;         const int j1 = j + 1;
;         const bool near1 = (64 * j1 + 63 >= qblk - 128) && (64 * j1 <= qblk + 255);
;         const float bc1 = tbl[(64 * j1 > qblk) ? 256 : 0]; const int dtoff1 = (64 * j1 > qblk) ? DA_DR_OFF : DA_DL_OFF;
;         DA_STEP(sa, sb, pp0, pp1, pc0, pc1, lds + bprev, 1, lds + bcur, 1, j * 64, lds + bcur, 0);
;         __syncthreads();
;         DA_STORE(lds + bnn); { const int jl = j + 3 < 64 ? j + 3 : 63; DA_LOAD(jl); }
;         DA_STEP(sb, sa, pc0, pc1, pp0, pp1, lds + bcur, 0, lds + bnext, 0, j * 64 + 32, lds + bcur, 1);
.LBB0_177:
	v_add_u32_e32 v64, s87, v175
	s_waitcnt lgkmcnt(0)
	s_barrier
	s_waitcnt vmcnt(3)
	ds_write_b128 v64, v[116:119]
	s_waitcnt vmcnt(2)
	ds_write_b128 v64, v[124:127] offset:8704
	v_add_u32_e32 v64, s87, v184
	s_min_u32 s7, s37, 60
	s_waitcnt vmcnt(0)
	v_perm_b32 v65, v120, v112, s66
	v_perm_b32 v66, v120, v112, s67
	v_add_u32_e32 v64, 0x4400, v64
	s_lshl_b32 s7, s7, 19
	ds_write2_b32 v64, v65, v66 offset1:32
	v_add_u32_e32 v65, s87, v185
	s_add_u32 s7, s30, s7
	v_perm_b32 v66, v121, v113, s66
	v_perm_b32 v67, v121, v113, s67
	v_add_u32_e32 v65, 0x4400, v65
	s_addc_u32 s9, s31, 0
	ds_write2_b32 v65, v66, v67 offset0:64 offset1:96
	v_perm_b32 v66, v122, v114, s66
	v_perm_b32 v67, v122, v114, s67
	s_add_u32 s8, s7, 0x180000
	ds_write2_b32 v64, v66, v67 offset0:128 offset1:160
	v_perm_b32 v64, v123, v115, s66
	v_perm_b32 v66, v123, v115, s67
	s_addc_u32 s9, s9, 0
	ds_write2_b32 v65, v64, v66 offset0:192 offset1:224
	global_load_dwordx4 v[116:119], v254, s[8:9]
	global_load_dwordx4 v[120:123], v169, s[8:9]
	global_load_dwordx4 v[112:115], v173, s[8:9]
	global_load_dwordx4 v[124:127], v171, s[8:9]
	s_cmp_gt_i32 s85, s77
	s_cselect_b64 s[8:9], -1, 0
	s_addk_i32 s86, 0xff81
	s_cmpk_gt_i32 s86, 0x7f
	s_cselect_b64 s[86:87], -1, 0
	s_or_b64 s[8:9], s[8:9], s[86:87]
	s_and_b64 vcc, exec, s[8:9]
	s_cbranch_vccnz .LBB0_179
	s_addk_i32 s6, 0x600
	v_add_u32_e32 v78, s6, v189
	ds_read2_b32 v[64:65], v78 offset0:48 offset1:49
	ds_read2_b32 v[66:67], v78 offset0:50 offset1:51
	ds_read2_b32 v[68:69], v78 offset0:56 offset1:57
	ds_read2_b32 v[70:71], v78 offset0:58 offset1:59
	ds_read2_b32 v[72:73], v78 offset0:32 offset1:33
	ds_read2_b32 v[74:75], v78 offset0:34 offset1:35
	ds_read2_b32 v[76:77], v78 offset0:40 offset1:41
	ds_read2_b32 v[78:79], v78 offset0:42 offset1:43
	s_waitcnt lgkmcnt(4)
	v_pk_add_f32 v[94:95], v[94:95], v[70:71]
	v_pk_add_f32 v[92:93], v[92:93], v[68:69]
	v_pk_add_f32 v[90:91], v[90:91], v[66:67]
	v_pk_add_f32 v[88:89], v[88:89], v[64:65]
	s_waitcnt lgkmcnt(0)
	v_pk_add_f32 v[86:87], v[86:87], v[78:79]
	v_pk_add_f32 v[84:85], v[84:85], v[76:77]
	v_pk_add_f32 v[82:83], v[82:83], v[74:75]
	v_pk_add_f32 v[80:81], v[80:81], v[72:73]

; __global__ void __launch_bounds__(512, 2) fwd_megakernel(Args a) {
	.amdhsa_kernel _Z14fwd_megakernel4Args
		.amdhsa_group_segment_fixed_size 0
		.amdhsa_private_segment_fixed_size 0
		.amdhsa_kernarg_size 384
		.amdhsa_user_sgpr_count 2
		.amdhsa_user_sgpr_dispatch_ptr 0
		.amdhsa_user_sgpr_queue_ptr 0
		.amdhsa_user_sgpr_kernarg_segment_ptr 1
		.amdhsa_user_sgpr_dispatch_id 0
		.amdhsa_user_sgpr_kernarg_preload_length 0
		.amdhsa_user_sgpr_kernarg_preload_offset 0
		.amdhsa_user_sgpr_private_segment_size 0
		.amdhsa_uses_dynamic_stack 0
		.amdhsa_enable_private_segment 0
		.amdhsa_system_sgpr_workgroup_id_x 1
		.amdhsa_system_sgpr_workgroup_id_y 0
		.amdhsa_system_sgpr_workgroup_id_z 0
		.amdhsa_system_sgpr_workgroup_info 0
		.amdhsa_system_vgpr_workitem_id 2
		.amdhsa_next_free_vgpr 256
		.amdhsa_next_free_sgpr 100
		.amdhsa_accum_offset 256
		.amdhsa_reserve_vcc 1
		.amdhsa_float_round_mode_32 0
		.amdhsa_float_round_mode_16_64 0
		.amdhsa_float_denorm_mode_32 3
		.amdhsa_float_denorm_mode_16_64 3
		.amdhsa_dx10_clamp 1
		.amdhsa_ieee_mode 1
		.amdhsa_fp16_overflow 0
		.amdhsa_tg_split 0
		.amdhsa_exception_fp_ieee_invalid_op 0
		.amdhsa_exception_fp_denorm_src 0
		.amdhsa_exception_fp_ieee_div_zero 0
		.amdhsa_exception_fp_ieee_overflow 0
		.amdhsa_exception_fp_ieee_underflow 0
		.amdhsa_exception_fp_ieee_inexact 0
		.amdhsa_exception_int_div_zero 0
	.end_amdhsa_kernel

; __global__ void __launch_bounds__(512, 2) fwd_megakernel(Args a) {
amdhsa.kernels:
  - .agpr_count:     0
    .args:
      - .offset:         0
        .size:           128
        .value_kind:     by_value
      - .offset:         128
        .size:           4
        .value_kind:     hidden_block_count_x
      - .offset:         132
        .size:           4
        .value_kind:     hidden_block_count_y
      - .offset:         136
        .size:           4
        .value_kind:     hidden_block_count_z
      - .offset:         140
        .size:           2
        .value_kind:     hidden_group_size_x
      - .offset:         142
        .size:           2
        .value_kind:     hidden_group_size_y
      - .offset:         144
        .size:           2
        .value_kind:     hidden_group_size_z
      - .offset:         146
        .size:           2
        .value_kind:     hidden_remainder_x
      - .offset:         148
        .size:           2
        .value_kind:     hidden_remainder_y
      - .offset:         150
        .size:           2
        .value_kind:     hidden_remainder_z
      - .offset:         168
        .size:           8
        .value_kind:     hidden_global_offset_x
      - .offset:         176
        .size:           8
        .value_kind:     hidden_global_offset_y
      - .offset:         184
        .size:           8
        .value_kind:     hidden_global_offset_z
      - .offset:         192
        .size:           2
        .value_kind:     hidden_grid_dims
      - .offset:         216
        .size:           8
        .value_kind:     hidden_multigrid_sync_arg
      - .offset:         248
        .size:           4
        .value_kind:     hidden_dynamic_lds_size
    .group_segment_fixed_size: 0
    .kernarg_segment_align: 8
    .kernarg_segment_size: 384
    .language:       OpenCL C
    .language_version:
      - 2
      - 0
    .max_flat_workgroup_size: 512
    .name:           _Z14fwd_megakernel4Args
    .private_segment_fixed_size: 0
    .sgpr_count:     106
    .sgpr_spill_count: 107
    .symbol:         _Z14fwd_megakernel4Args.kd
    .uniform_work_group_size: 1
    .uses_dynamic_stack: false
    .vgpr_count:     256
    .vgpr_spill_count: 0
    .wavefront_size: 64
